# even-mixer conv: part-per-wave remap (k waves alone on SIMD2/3), pass 1 reuses pass-0 loaded weights/rows, v-part waves skip pass-0 compute
# speedup vs baseline: 1.0579x; 1.0041x over previous
; #define LAS __attribute__((address_space(3)))
; __device__ __forceinline__ void phase_even_mix(const int wid_s, CParams& p, int j, LAS unsigned char* lds) {
;     ...
;             int tidc_ = tidi_; asm volatile("" : "+v"(tidc_));
;             const int tid = tidc_, lane = tid & 63, wave = tid >> 6, lr = lane & 15, lq = lane >> 4;
;             const int tc0 = t0 + cc * 64; const int tin = (n * 128 + cc * 64);
;             const int chh = (tc0 >> 6) * 4 + h;
;             if (tid < 128) ssq[tid] = 0.f;
;             __syncthreads();
;             LAS h16* KDs = (LAS h16*)(lds + EM_LM);
; #pragma unroll 1
;             for (int pass = 0; pass < 2; ++pass) {
;                 if (tid < 384) {
;                     const int gq = tid % 48, part = gq >> 4, c8 = (gq & 15) * 8, tok8 = (tid / 48) * 8;
;                     float wv[4][8];
; #pragma unroll
;                     for (int jj = 0; jj < 4; ++jj)
; #pragma unroll
;                         for (int e = 0; e < 8; ++e) wv[jj][e] = cw[jj * 1536 + part * 512 + h * 128 + c8 + e];
;                     const h16* xp = proj + (size_t)tc0 * EV_N + 1024 + part * 512 + h * 128 + c8;
;                     const float glast = pass ? gcs[63] : 0.f;
;                     h16x8 xa[11];
; #pragma unroll
;                     for (int r = 0; r < 11; ++r) { const int tt = tok8 - 3 + r; const bool okr = tin + tt >= 0;
;                         xa[r] = *(const h16x8*)(xp + (long)(okr ? tt : 0) * EV_N);
;                         if (!okr) {
; #pragma unroll
;                             for (int e = 0; e < 8; ++e) xa[r][e] = (h16)0.f; } }
.LBB0_1064:
	v_mov_b32_e32 v154, v153
	s_movk_i32 s6, 0x80
	s_nop 0
	v_cmp_gt_i32_e32 vcc, s6, v154
	s_and_saveexec_b64 s[6:7], vcc
	v_lshl_add_u32 v0, v154, 2, 0
	v_add_u32_e32 v0, 0x23400, v0
	ds_write_b32 v0, v1
	s_or_b64 exec, exec, s[6:7]
	s_xor_b64 s[84:85], s[4:5], -1
	v_readlane_b32 s4, v252, 43
	s_or_b32 s64, s12, s4
	s_ashr_i32 s4, s64, 4
	v_readlane_b32 s5, v252, 19
	s_or_b32 s90, s4, s5
	s_movk_i32 s4, 0x17f
	v_add_u32_e32 v0, 0xfffffe80, v154
	v_cmp_lt_i32_e64 s[6:7], s4, v154
	s_movk_i32 s4, 0x1c0
	v_add_u32_e32 v2, s64, v0
	v_cmp_gt_u32_e64 s[8:9], s4, v154
	v_ashrrev_i32_e32 v3, 31, v2
	v_readlane_b32 s4, v252, 47
	v_lshlrev_b64 v[2:3], 5, v[2:3]
	v_readlane_b32 s5, v252, 48
	s_ashr_i32 s91, s90, 31
	v_readlane_b32 s13, v252, 30
	v_lshl_add_u64 v[78:79], s[4:5], 0, v[2:3]
	v_lshlrev_b32_e32 v2, 2, v0
	v_readlane_b32 s4, v252, 5
	v_cmp_eq_u32_e64 s[10:11], 63, v0
	s_movk_i32 s54, 0x1a00
	v_add_u32_e32 v155, s4, v2
	v_readlane_b32 s4, v252, 6
	s_movk_i32 s82, 0x48
	s_waitcnt lgkmcnt(0)
	v_add_u32_e32 v162, s4, v2
	s_lshl_b64 s[4:5], s[90:91], 2
	s_add_u32 s92, s13, s4
	v_readlane_b32 s4, v252, 31
	s_addc_u32 s93, s4, s5
	v_lshrrev_b32_e32 v4, 7, v154
	v_and_b32_e32 v6, 0x7f, v154
	v_lshrrev_b32_e32 v7, 4, v6
	v_and_b32_e32 v6, 15, v6
	v_mul_u32_u24_e32 v7, 48, v7
	v_lshl_add_u32 v6, v4, 4, v6
	v_add_u32_e32 v8, v7, v6
	s_mov_b32 s4, 0x2aaaaaab
	v_mul_hi_i32 v0, v8, s4
	v_lshrrev_b32_e32 v2, 31, v0
	v_ashrrev_i32_e32 v0, 3, v0
	v_add_u32_e32 v0, v0, v2
	v_mul_lo_u32 v2, v0, 48
	v_sub_u32_e32 v5, v8, v2
	v_ashrrev_i32_e32 v6, 4, v5
	v_lshlrev_b32_e32 v2, 3, v5
	s_mul_i32 s4, s64, 0x1a00
	v_and_b32_e32 v7, 0x78, v2
	v_lshlrev_b32_e32 v2, 9, v6
	s_mul_hi_i32 s5, s64, 0x1a00
	s_add_u32 s4, s86, s4
	s_addc_u32 s5, s87, s5
	v_ashrrev_i32_e32 v3, 31, v2
	v_or3_b32 v4, v2, s83, v7
	v_lshl_add_u64 v[2:3], v[2:3], 1, s[4:5]
	v_readlane_b32 s4, v252, 46
	s_nor_b32 s52, s12, s4
	v_readlane_b32 s4, v252, 49
	v_lshlrev_b32_e32 v163, 3, v0
	v_lshlrev_b32_e32 v0, 1, v7
	v_readlane_b32 s5, v252, 50
	v_cmp_lt_u32_e64 s[12:13], 15, v5
	v_ashrrev_i32_e32 v5, 31, v4
	v_lshl_add_u64 v[80:81], s[4:5], 0, v[0:1]
	s_movk_i32 s4, 0x180
	v_cmp_eq_u32_e64 s[18:19], s4, v154
	s_movk_i32 s4, 0x182
	v_cmp_gt_u32_e64 s[20:21], s4, v154
	s_movk_i32 s4, 0x184
	v_cmp_gt_u32_e64 s[22:23], s4, v154
	s_movk_i32 s4, 0x188
	v_cmp_gt_u32_e64 s[24:25], s4, v154
	s_movk_i32 s4, 0x190
	v_cmp_gt_u32_e64 s[26:27], s4, v154
	s_movk_i32 s4, 0x1a0
	v_cmp_gt_u32_e64 s[28:29], s4, v154
	v_readlane_b32 s4, v252, 36
	v_readlane_b32 s5, v252, 37
	v_add_u32_e32 v8, -3, v163
	v_lshl_add_u64 v[2:3], v[2:3], 0, s[58:59]
	v_lshl_add_u64 v[82:83], v[4:5], 2, s[4:5]
	s_mov_b64 s[4:5], 0x1800
	v_lshl_add_u64 v[84:85], v[82:83], 0, s[4:5]
	s_mov_b64 s[4:5], 0x3000
	v_cmp_lt_i32_e64 s[30:31], s52, v8
	v_lshl_add_u64 v[2:3], v[2:3], 0, v[0:1]
	v_add_u32_e32 v76, 0, v0
	v_lshl_add_u64 v[86:87], v[82:83], 0, s[4:5]
	s_mov_b64 s[4:5], 0x4800
	v_cndmask_b32_e64 v0, 0, v8, s[30:31]
	v_lshl_add_u64 v[88:89], v[82:83], 0, s[4:5]
	v_mad_i64_i32 v[90:91], s[4:5], v0, s54, v[2:3]
	v_add_u32_e32 v0, -2, v163
	v_cmp_lt_i32_e64 s[34:35], s52, v0
	v_cmp_lt_i32_e64 s[38:39], s52, v163
	v_cmp_gt_i32_e64 s[40:41], s52, v163
	v_cndmask_b32_e64 v0, 0, v0, s[34:35]
	v_mad_i64_i32 v[92:93], s[4:5], v0, s54, v[2:3]
	v_add_u32_e32 v0, -1, v163
	v_cmp_lt_i32_e64 s[36:37], s52, v0
	s_add_i32 s65, 0, 0x23400
	v_cmp_ne_u32_e64 s[14:15], 1, v6
	v_cndmask_b32_e64 v0, 0, v0, s[36:37]
	v_mad_i64_i32 v[94:95], s[4:5], v0, s54, v[2:3]
	v_cndmask_b32_e64 v0, 0, v163, s[38:39]
	v_mad_i64_i32 v[96:97], s[4:5], v0, s54, v[2:3]
	v_or_b32_e32 v0, 1, v163
	v_cndmask_b32_e64 v0, v0, 0, s[40:41]
	v_mad_i64_i32 v[98:99], s[4:5], v0, s54, v[2:3]
	v_or_b32_e32 v0, 2, v163
	v_cmp_lt_i32_e64 s[42:43], s52, v0
	v_cmp_gt_i32_e64 s[16:17], 2, v6
	v_lshl_add_u32 v164, v6, 8, s65
	v_cndmask_b32_e64 v0, 0, v0, s[42:43]
	v_mad_i64_i32 v[100:101], s[4:5], v0, s54, v[2:3]
	v_or_b32_e32 v0, 3, v163
	v_cmp_lt_i32_e64 s[44:45], s52, v0
	v_mul_u32_u24_e32 v165, 0x48, v7
	s_barrier
	v_cndmask_b32_e64 v0, 0, v0, s[44:45]
	v_mad_i64_i32 v[102:103], s[4:5], v0, s54, v[2:3]
	v_or_b32_e32 v0, 4, v163
	v_cmp_lt_i32_e64 s[46:47], s52, v0
	s_nop 1
	v_cndmask_b32_e64 v0, 0, v0, s[46:47]
	v_mad_i64_i32 v[104:105], s[4:5], v0, s54, v[2:3]
	v_or_b32_e32 v0, 5, v163
	v_cmp_lt_i32_e64 s[48:49], s52, v0
	s_nop 1
	v_cndmask_b32_e64 v0, 0, v0, s[48:49]
	v_mad_i64_i32 v[106:107], s[4:5], v0, s54, v[2:3]
	v_or_b32_e32 v0, 6, v163
	v_cmp_lt_i32_e64 s[50:51], s52, v0
	s_nop 1
	v_cndmask_b32_e64 v0, 0, v0, s[50:51]
	v_mad_i64_i32 v[108:109], s[4:5], v0, s54, v[2:3]
	v_or_b32_e32 v0, 7, v163
	v_cmp_lt_i32_e64 s[52:53], s52, v0
	s_nop 1
	v_cndmask_b32_e64 v0, 0, v0, s[52:53]
	v_mad_i64_i32 v[110:111], s[4:5], v0, s54, v[2:3]
	s_movk_i32 s4, 0x48
	v_mov_b32_e32 v0, 0x90
	v_mad_u32_u24 v167, v7, s4, v0
	v_mov_b32_e32 v0, 0xd8
	v_mad_u32_u24 v168, v7, s4, v0
	v_mov_b32_e32 v0, 0x120
	v_mad_u32_u24 v169, v7, s4, v0
	v_mov_b32_e32 v0, 0x168
	v_mad_u32_u24 v170, v7, s4, v0
	v_mov_b32_e32 v0, 0x1b0
	v_mad_u32_u24 v171, v7, s4, v0
	v_mov_b32_e32 v0, 0x1f8
	v_mad_u32_u24 v166, v7, s4, s4
	v_mad_u32_u24 v172, v7, s4, v0
	v_readlane_b32 s4, v252, 7
	s_mov_b64 s[54:55], -1
	s_nop 0
	v_mov_b32_e32 v0, s4
	v_mad_u32_u24 v173, v7, s60, v0
	s_branch .LBB0_1068

; __device__ __forceinline__ void phase_even_mix(const int wid_s, CParams& p, int j, LAS unsigned char* lds) {
;     ...
;             for (int pass = 0; pass < 2; ++pass) {
;                 if (tid < 384) {
;                     const int gq = tid % 48, part = gq >> 4, c8 = (gq & 15) * 8, tok8 = (tid / 48) * 8;
;                     float wv[4][8];
; #pragma unroll
;                     for (int jj = 0; jj < 4; ++jj)
; #pragma unroll
;                         for (int e = 0; e < 8; ++e) wv[jj][e] = cw[jj * 1536 + part * 512 + h * 128 + c8 + e];
;                     const h16* xp = proj + (size_t)tc0 * EV_N + 1024 + part * 512 + h * 128 + c8;
;                     const float glast = pass ? gcs[63] : 0.f;
;                     h16x8 xa[11];
; #pragma unroll
;                     for (int r = 0; r < 11; ++r) { const int tt = tok8 - 3 + r; const bool okr = tin + tt >= 0;
;                         xa[r] = *(const h16x8*)(xp + (long)(okr ? tt : 0) * EV_N);
;                         if (!okr) {
; #pragma unroll
;                             for (int e = 0; e < 8; ++e) xa[r][e] = (h16)0.f; } }
.LBB0_1075:
	s_or_saveexec_b64 s[66:67], s[4:5]
	s_xor_b64 s[4:5], s[54:55], -1
	s_xor_b64 exec, exec, s[66:67]
	s_cbranch_execz .LBB0_1067
	s_cmp_lg_u64 s[4:5], 0
	s_cbranch_scc1 .Levmix_pass1
	global_load_dwordx4 v[2:5], v[82:83], off offset:16
	global_load_dwordx4 v[6:9], v[82:83], off
	global_load_dwordx4 v[10:13], v[84:85], off offset:16
	global_load_dwordx4 v[14:17], v[84:85], off
	global_load_dwordx4 v[18:21], v[86:87], off offset:16
	global_load_dwordx4 v[22:25], v[86:87], off
	global_load_dwordx4 v[26:29], v[88:89], off offset:16
	global_load_dwordx4 v[30:33], v[88:89], off
	v_cndmask_b32_e64 v0, 0, 1, s[4:5]
	v_cmp_ne_u32_e64 s[54:55], 1, v0
	s_andn2_b64 vcc, exec, s[4:5]
	v_mov_b32_e32 v161, 0
	s_cbranch_vccnz .LBB0_1078
	v_readlane_b32 s56, v252, 8
	s_nop 1
	v_mov_b32_e32 v0, s56
	ds_read_b32 v161, v0
.LBB0_1078:
	global_load_dwordx4 v[36:39], v[90:91], off offset:2048
	global_load_dwordx4 v[40:43], v[92:93], off offset:2048
	global_load_dwordx4 v[44:47], v[94:95], off offset:2048
	global_load_dwordx4 v[48:51], v[96:97], off offset:2048
	global_load_dwordx4 v[52:55], v[98:99], off offset:2048
	global_load_dwordx4 v[56:59], v[100:101], off offset:2048
	global_load_dwordx4 v[60:63], v[102:103], off offset:2048
	global_load_dwordx4 v[64:67], v[104:105], off offset:2048
	global_load_dwordx4 v[68:71], v[106:107], off offset:2048
	global_load_dwordx4 v[72:75], v[108:109], off offset:2048
	global_load_dwordx4 v[112:115], v[110:111], off offset:2048
	s_mov_b32 s56, 0
	s_mov_b64 s[76:77], -1
	s_waitcnt vmcnt(10)
	v_cndmask_b32_e64 v35, 0, v39, s[30:31]
	v_cndmask_b32_e64 v34, 0, v38, s[30:31]
	v_cndmask_b32_e64 v37, 0, v37, s[30:31]
	v_cndmask_b32_e64 v0, 0, v36, s[30:31]
	s_waitcnt vmcnt(9)
	v_cndmask_b32_e64 v39, 0, v43, s[34:35]
	v_cndmask_b32_e64 v36, 0, v42, s[34:35]
	v_cndmask_b32_e64 v41, 0, v41, s[34:35]
	v_cndmask_b32_e64 v38, 0, v40, s[34:35]
	s_waitcnt vmcnt(8)
	v_cndmask_b32_e64 v43, 0, v47, s[36:37]
	v_cndmask_b32_e64 v40, 0, v46, s[36:37]
	v_cndmask_b32_e64 v45, 0, v45, s[36:37]
	v_cndmask_b32_e64 v42, 0, v44, s[36:37]
	s_waitcnt vmcnt(7)
	v_cndmask_b32_e64 v47, 0, v51, s[38:39]
	v_cndmask_b32_e64 v44, 0, v50, s[38:39]
	v_cndmask_b32_e64 v49, 0, v49, s[38:39]
	v_cndmask_b32_e64 v46, 0, v48, s[38:39]
	s_waitcnt vmcnt(6)
	v_cndmask_b32_e64 v51, v55, 0, s[40:41]
	v_cndmask_b32_e64 v48, v54, 0, s[40:41]
	v_cndmask_b32_e64 v53, v53, 0, s[40:41]
	v_cndmask_b32_e64 v50, v52, 0, s[40:41]
	s_waitcnt vmcnt(5)
	v_cndmask_b32_e64 v55, 0, v59, s[42:43]
	v_cndmask_b32_e64 v52, 0, v58, s[42:43]
	v_cndmask_b32_e64 v57, 0, v57, s[42:43]
	v_cndmask_b32_e64 v54, 0, v56, s[42:43]
	s_waitcnt vmcnt(4)
	v_cndmask_b32_e64 v59, 0, v63, s[44:45]
	v_cndmask_b32_e64 v56, 0, v62, s[44:45]
	v_cndmask_b32_e64 v61, 0, v61, s[44:45]
	v_cndmask_b32_e64 v58, 0, v60, s[44:45]
	s_waitcnt vmcnt(3)
	v_cndmask_b32_e64 v63, 0, v67, s[46:47]
	v_cndmask_b32_e64 v60, 0, v66, s[46:47]
	v_cndmask_b32_e64 v65, 0, v65, s[46:47]
	v_cndmask_b32_e64 v62, 0, v64, s[46:47]
	s_waitcnt vmcnt(2)
	v_cndmask_b32_e64 v67, 0, v71, s[48:49]
	v_cndmask_b32_e64 v64, 0, v70, s[48:49]
	v_cndmask_b32_e64 v69, 0, v69, s[48:49]
	v_cndmask_b32_e64 v66, 0, v68, s[48:49]
	s_waitcnt vmcnt(1)
	v_cndmask_b32_e64 v71, 0, v75, s[50:51]
	v_cndmask_b32_e64 v68, 0, v74, s[50:51]
	v_cndmask_b32_e64 v73, 0, v73, s[50:51]
	v_cndmask_b32_e64 v70, 0, v72, s[50:51]
	s_waitcnt vmcnt(0)
	v_cndmask_b32_e64 v75, 0, v115, s[52:53]
	v_cndmask_b32_e64 v72, 0, v114, s[52:53]
	v_cndmask_b32_e64 v77, 0, v113, s[52:53]
	v_cndmask_b32_e64 v74, 0, v112, s[52:53]
	v_readfirstlane_b32 s57, v154
	s_lshr_b32 s57, s57, 7
	s_cmp_eq_u32 s57, 2
	s_cbranch_scc1 .LBB0_1067
	s_branch .LBB0_1081
.Levmix_pass1:
	s_mov_b64 s[54:55], 0
	v_readlane_b32 s56, v252, 8
	s_nop 1
	v_mov_b32_e32 v112, s56
	ds_read_b32 v161, v112
	s_mov_b32 s56, 0
	s_mov_b64 s[76:77], -1
	s_branch .LBB0_1081
